# L1 invalidates of the count-in barriers issued at count-in time (their latency hides behind the filler work); adaLN wait: invalidate before the poll
# baseline (speedup 1.0000x reference)
.LBB0_47:
	s_cmp_lg_u32 s100, 0
	s_cbranch_scc1 .Lsb1_wait
	s_cmp_lt_i32 s94, 2
	s_cselect_b64 s[0:1], -1, 0
	s_cmp_gt_i32 s95, 1
	s_cselect_b64 s[8:9], -1, 0
	s_and_b64 s[0:1], s[0:1], s[8:9]
	s_andn2_b64 vcc, exec, s[0:1]
	s_cbranch_vccnz .LBB0_70
	s_mov_b64 s[8:9], exec
	v_readlane_b32 s10, v246, 2
	v_readlane_b32 s11, v246, 3
	s_and_b64 s[10:11], s[8:9], s[10:11]
	s_mov_b64 exec, s[10:11]
	s_cbranch_execz .LBB0_58
	buffer_inv sc1
	s_min_i32 s5, s3, 0xc0
	s_add_u32 s10, s92, 0x3800
	s_addc_u32 s11, s93, 0
	s_mov_b32 s7, 0x400001
	v_mov_b32_e32 v2, 0
	s_branch .LBB0_51

.LBB0_51:
	global_load_dword v3, v2, s[10:11] sc1
	s_waitcnt lgkmcnt(0)
	s_mov_b64 s[14:15], -1
	s_waitcnt vmcnt(0)
	v_cmp_le_u32_e32 vcc, s5, v3
	s_cbranch_vccnz .LBB0_50
	s_sleep 1
	global_load_dword v3, v2, s[10:11] sc1
	s_waitcnt vmcnt(0)
	v_cmp_gt_u32_e32 vcc, s5, v3
	s_cbranch_vccz .LBB0_50
	s_sleep 1
	global_load_dword v3, v2, s[10:11] sc1
	s_waitcnt vmcnt(0)
	v_cmp_gt_u32_e32 vcc, s5, v3
	s_cbranch_vccz .LBB0_50
	s_sleep 1
	global_load_dword v3, v2, s[10:11] sc1
	s_waitcnt vmcnt(0)
	v_cmp_gt_u32_e32 vcc, s5, v3
	s_cbranch_vccz .LBB0_50
	s_sleep 1
	global_load_dword v3, v2, s[10:11] sc1
	s_waitcnt vmcnt(0)
	v_cmp_gt_u32_e32 vcc, s5, v3
	s_cbranch_vccz .LBB0_50
	s_add_i32 s7, s7, -5
	s_cmp_eq_u32 s7, 0
	s_cselect_b64 s[14:15], -1, 0
	s_sleep 1
	s_branch .LBB0_50
.LBB0_57:
	s_waitcnt vmcnt(0)
.LBB0_58:
	s_or_b64 exec, exec, s[8:9]
	s_waitcnt lgkmcnt(0)
	s_add_u32 s19, s92, 0x40000
	s_addc_u32 s20, s93, 0
	s_abs_i32 s5, s6
	v_cvt_f32_u32_e32 v2, s5
	s_sub_i32 s8, 0, s5
	s_ashr_i32 s7, s6, 31
	v_lshlrev_b32_e32 v22, 2, v1
	v_rcp_iflag_f32_e32 v2, v2
	v_mov_b32_e32 v11, 0
	v_lshlrev_b32_e32 v10, 4, v1
	v_mov_b32_e32 v7, v11
	v_mul_f32_e32 v2, 0x4f7ffffe, v2
	v_cvt_u32_f32_e32 v2, v2
	v_mov_b32_e32 v5, v11
	v_mov_b32_e32 v3, v11
	v_readfirstlane_b32 s9, v2
	s_mul_i32 s8, s8, s9
	s_mul_hi_u32 s8, s9, s8
	s_add_i32 s9, s9, s8
	s_lshr_b32 s8, s9, 18
	s_mul_i32 s9, s8, s5
	s_sub_i32 s9, 0x4000, s9
	s_add_i32 s10, s8, 1
	s_sub_i32 s11, s9, s5
	s_cmp_ge_u32 s9, s5
	s_cselect_b32 s8, s10, s8
	s_cselect_b32 s9, s11, s9
	s_add_i32 s10, s8, 1
	s_cmp_ge_u32 s9, s5
	s_cselect_b32 s5, s10, s8
	s_xor_b32 s5, s5, s7
	s_sub_i32 s18, s5, s7
	s_mul_i32 s5, s18, s6
	v_or_b32_e32 v2, 0x100, v22
	s_cmpk_lg_i32 s5, 0x4000
	v_lshlrev_b32_e32 v6, 2, v2
	v_or_b32_e32 v2, 0x200, v22
	s_cselect_b64 s[10:11], -1, 0
	s_add_u32 s8, s80, 0x1000
	v_lshlrev_b32_e32 v4, 2, v2
	v_or_b32_e32 v2, 0x300, v22
	s_addc_u32 s9, s81, 0
	v_lshlrev_b32_e32 v2, 2, v2
	s_and_b64 vcc, exec, s[10:11]
	s_barrier
	s_cbranch_vccnz .LBB0_60
	v_cvt_f32_i32_e32 v8, s18
	s_mov_b32 s10, 0x46000000
	s_ashr_i32 s5, s18, 30
	s_or_b32 s5, s5, 1
	v_rcp_iflag_f32_e32 v9, v8
	s_nop 0
	v_mul_f32_e32 v12, 0x46000000, v9
	v_trunc_f32_e32 v12, v12
	v_fma_f32 v13, -v12, v8, s10
	v_cvt_i32_f32_e32 v12, v12
	v_cmp_ge_f32_e64 s[10:11], |v13|, |v8|
	s_and_b64 s[10:11], s[10:11], exec
	s_cselect_b32 s10, s5, 0
	v_readfirstlane_b32 s11, v12
	s_add_i32 s10, s11, s10
	s_mul_i32 s10, s10, s18
	s_sub_i32 s10, 0x2000, s10
	s_and_b32 s14, s10, 0xffff
	s_cmp_lg_u32 s14, 0
	s_cselect_b64 s[10:11], -1, 0
	s_cmp_eq_u32 s14, 0
	s_cbranch_scc1 .LBB0_82

.Lsb1_census_ok:
	buffer_inv sc1
	v_readlane_b32 s18, v4, s33
	s_nop 3
	v_writelane_b32 v246, s18, 8
	v_readfirstlane_b32 s19, v3
	s_add_u32 s19, s19, 1
	s_cmp_lg_u32 s19, s18
	s_cbranch_scc1 .Lsb1_arr_end
	buffer_wbl2 sc1
	s_waitcnt vmcnt(0)
	s_add_u32 s8, s92, 0x57000
	s_addc_u32 s9, s93, 0
	v_mov_b32_e32 v3, s18
	global_atomic_add v2, v3, s[8:9]

.Lsb1_wait:
	s_waitcnt vmcnt(0) lgkmcnt(0)
	s_barrier
	s_mov_b64 s[0:1], exec
	v_readlane_b32 s6, v246, 2
	v_readlane_b32 s7, v246, 3
	s_and_b64 s[6:7], s[0:1], s[6:7]
	s_mov_b64 exec, s[6:7]
	s_cbranch_execz .Lsb1_w_end
	s_add_u32 s8, s92, 0x57000
	s_addc_u32 s9, s93, 0
	v_mov_b32_e32 v2, 0
	s_mov_b32 s10, 0x400000
	s_movk_i32 s11, 0xff

.LBB0_134:
	s_add_i32 s79, s79, 1
	s_cmp_lg_u32 s79, 6
	s_cbranch_scc1 .Lp2_noarr
	s_mov_b64 s[100:101], exec
	v_readlane_b32 s4, v246, 2
	v_readlane_b32 s5, v246, 3
	s_and_b64 s[4:5], s[100:101], s[4:5]
	s_mov_b64 exec, s[4:5]
	s_cbranch_execz .Lp2_arr_done
	v_mov_b32_e32 v250, 0
	v_mov_b32_e32 v251, 1
	s_add_u32 s4, s92, 0x55000
	s_addc_u32 s5, s93, 0
	global_atomic_add v250, v251, s[4:5]
	buffer_inv sc1

.LBB0_190:
	s_cmp_gt_i32 s95, 3
	s_cselect_b64 s[0:1], -1, 0
	s_and_b64 s[4:5], s[6:7], s[0:1]
	s_andn2_b64 vcc, exec, s[4:5]
	s_cbranch_vccnz .LBB0_244
	s_waitcnt vmcnt(0) lgkmcnt(0)
	s_barrier
	s_mov_b64 s[4:5], exec
	v_readlane_b32 s6, v246, 2
	v_readlane_b32 s7, v246, 3
	s_and_b64 s[6:7], s[4:5], s[6:7]
	s_mov_b64 exec, s[6:7]
	s_cbranch_execz .Lp2w_end
	s_add_u32 s6, s92, 0x55000
	s_addc_u32 s7, s93, 0
	s_and_b32 s8, s2, 15
	s_lshl_b32 s8, s8, 2
	s_add_u32 s8, s8, 0x54200
	s_add_u32 s8, s92, s8
	s_addc_u32 s9, s93, 0
	v_mov_b32_e32 v2, 0
	s_mov_b32 s10, 0x400000
	s_movk_i32 s11, 0xff
